# LayerNorm exchange poll loop without the 128-cycle sleep between counter reads
# speedup vs baseline: 1.0100x; 1.0100x over previous
.LBB0_416:
	global_load_dword v132, v165, s[48:49] sc1
	s_mov_b64 s[50:51], -1
	s_mov_b64 s[52:53], -1
	s_waitcnt vmcnt(0)
	v_readfirstlane_b32 s15, v132
	s_cmp_gt_u32 s15, 31
	s_cbranch_scc1 .LBB0_415
	s_memrealtime s[50:51]
	s_waitcnt lgkmcnt(0)
	s_sub_u32 s50, s50, s46
	s_subb_u32 s51, s51, s47
	v_cmp_lt_u64_e32 vcc, s[50:51], v[174:175]
	s_cbranch_vccz .LBB0_414
	s_mov_b64 s[52:53], 0
	s_nop 0
	s_branch .LBB0_414
